# code placement: every hot K-loop head (P2..P8 main loops, both quarter loops) pinned to a 64-byte boundary with never-executed / once-per-tile s_nop padding
# speedup vs baseline: 1.0061x; 1.0046x over previous
.LBB0_180:
	s_add_i32 s85, s85, 1
	s_cmp_lt_i32 s85, s43
	s_cselect_b64 s[8:9], -1, 0
	s_cmp_eq_u32 s85, s43
	s_cselect_b64 s[26:27], -1, 0
	s_min_i32 s35, s85, s43
	s_mov_b32 s34, s70
	s_waitcnt lgkmcnt(0)
	s_mul_i32 s35, s35, s92
	v_readlane_b32 s70, v253, 44
	s_add_i32 s35, s35, s70
	s_min_i32 s35, s35, 0x40f
	s_ashr_i32 s70, s35, 31
	s_lshr_b32 s70, s70, 29
	s_add_i32 s70, s35, s70
	s_mov_b64 s[4:5], s[74:75]
	s_ashr_i32 s74, s70, 3
	s_and_b32 s70, s70, -8
	s_and_b64 s[26:27], s[26:27], s[68:69]
	s_sub_i32 s35, s35, s70
	s_cmp_lt_i32 s35, 0
	s_cselect_b32 s70, s45, 0x82
	s_mul_i32 s35, s35, s70
	s_add_i32 s35, s35, s74
	s_mul_hi_i32 s70, s35, 0xd20d20d3
	s_add_i32 s70, s70, s35
	s_lshr_b32 s74, s70, 31
	s_ashr_i32 s70, s70, 6
	s_add_i32 s70, s70, s74
	s_mov_b64 s[6:7], s[76:77]
	s_mul_i32 s76, s70, 3
	s_sub_i32 s74, 40, s76
	s_min_u32 s77, s74, 3
	s_mulk_i32 s70, 0x4e
	s_sub_i32 s86, s35, s70
	v_cvt_f32_ubyte0_e32 v1, s77
	v_cvt_f32_i32_e32 v0, s86
	v_rcp_iflag_f32_e32 v2, v1
	s_mov_b32 s35, s46
	s_ashr_i32 s46, s86, 30
	s_or_b32 s46, s46, 1
	v_mul_f32_e32 v2, v0, v2
	v_trunc_f32_e32 v2, v2
	v_fma_f32 v0, -v2, v1, v0
	v_cvt_i32_f32_e32 v2, v2
	v_cmp_ge_f32_e64 s[74:75], |v0|, v1
	s_and_b64 s[74:75], s[74:75], exec
	s_cselect_b32 s46, s46, 0
	v_readfirstlane_b32 s70, v2
	s_add_i32 s70, s70, s46
	s_mul_i32 s46, s70, s77
	s_sub_i32 s46, s86, s46
	s_sext_i32_i8 s46, s46
	s_add_i32 s46, s76, s46
	s_or_b64 s[92:93], s[8:9], s[26:27]
	s_lshl_b32 s8, s46, 8
	s_ashr_i32 s9, s8, 31
	s_lshl_b64 s[8:9], s[8:9], 12
	s_add_u32 s74, s36, s8
	s_addc_u32 s75, s37, s9
	s_and_b64 s[8:9], s[92:93], exec
	s_cselect_b32 s26, s75, s5
	s_cselect_b32 s27, s74, s4
	s_bfe_i64 s[8:9], s[70:71], 0x80000
	s_lshl_b64 s[8:9], s[8:9], 20
	s_add_u32 s76, s38, s8
	s_addc_u32 s77, s39, s9
	s_and_b64 s[8:9], s[92:93], exec
	s_cselect_b32 s86, s77, s7
	s_cselect_b32 s91, s76, s6
	s_add_u32 s4, s4, 0x80080
	s_addc_u32 s5, s5, 0
	s_add_u32 s94, s6, 0x100
	v_mov_b32_e32 v0, 0
	s_addc_u32 s95, s7, 0
	s_mov_b32 s96, -2
	v_mov_b32_e32 v1, v0
	v_mov_b32_e32 v2, v0
	v_mov_b32_e32 v3, v0
	v_mov_b32_e32 v4, v0
	v_mov_b32_e32 v5, v0
	v_mov_b32_e32 v6, v0
	v_mov_b32_e32 v7, v0
	v_mov_b32_e32 v16, v0
	v_mov_b32_e32 v17, v0
	v_mov_b32_e32 v18, v0
	v_mov_b32_e32 v19, v0
	v_mov_b32_e32 v20, v0
	v_mov_b32_e32 v21, v0
	v_mov_b32_e32 v22, v0
	v_mov_b32_e32 v23, v0
	v_mov_b32_e32 v32, v0
	v_mov_b32_e32 v33, v0
	v_mov_b32_e32 v34, v0
	v_mov_b32_e32 v35, v0
	v_mov_b32_e32 v36, v0
	v_mov_b32_e32 v37, v0
	v_mov_b32_e32 v38, v0
	v_mov_b32_e32 v39, v0
	v_mov_b32_e32 v48, v0
	v_mov_b32_e32 v49, v0
	v_mov_b32_e32 v50, v0
	v_mov_b32_e32 v51, v0
	v_mov_b32_e32 v52, v0
	v_mov_b32_e32 v53, v0
	v_mov_b32_e32 v54, v0
	v_mov_b32_e32 v55, v0
	v_mov_b32_e32 v8, v0
	v_mov_b32_e32 v9, v0
	v_mov_b32_e32 v10, v0
	v_mov_b32_e32 v11, v0
	v_mov_b32_e32 v12, v0
	v_mov_b32_e32 v13, v0
	v_mov_b32_e32 v14, v0
	v_mov_b32_e32 v15, v0
	v_mov_b32_e32 v24, v0
	v_mov_b32_e32 v25, v0
	v_mov_b32_e32 v26, v0
	v_mov_b32_e32 v27, v0
	v_mov_b32_e32 v28, v0
	v_mov_b32_e32 v29, v0
	v_mov_b32_e32 v30, v0
	v_mov_b32_e32 v31, v0
	v_mov_b32_e32 v40, v0
	v_mov_b32_e32 v41, v0
	v_mov_b32_e32 v42, v0
	v_mov_b32_e32 v43, v0
	v_mov_b32_e32 v44, v0
	v_mov_b32_e32 v45, v0
	v_mov_b32_e32 v46, v0
	v_mov_b32_e32 v47, v0
	v_mov_b32_e32 v56, v0
	v_mov_b32_e32 v57, v0
	v_mov_b32_e32 v58, v0
	v_mov_b32_e32 v59, v0
	v_mov_b32_e32 v60, v0
	v_mov_b32_e32 v61, v0
	v_mov_b32_e32 v62, v0
	v_mov_b32_e32 v63, v0
	v_mov_b32_e32 v64, v0
	v_mov_b32_e32 v65, v0
	v_mov_b32_e32 v66, v0
	v_mov_b32_e32 v67, v0
	v_mov_b32_e32 v68, v0
	v_mov_b32_e32 v69, v0
	v_mov_b32_e32 v70, v0
	v_mov_b32_e32 v71, v0
	v_mov_b32_e32 v80, v0
	v_mov_b32_e32 v81, v0
	v_mov_b32_e32 v82, v0
	v_mov_b32_e32 v83, v0
	v_mov_b32_e32 v84, v0
	v_mov_b32_e32 v85, v0
	v_mov_b32_e32 v86, v0
	v_mov_b32_e32 v87, v0
	v_mov_b32_e32 v96, v0
	v_mov_b32_e32 v97, v0
	v_mov_b32_e32 v98, v0
	v_mov_b32_e32 v99, v0
	v_mov_b32_e32 v100, v0
	v_mov_b32_e32 v101, v0
	v_mov_b32_e32 v102, v0
	v_mov_b32_e32 v103, v0
	v_mov_b32_e32 v112, v0
	v_mov_b32_e32 v113, v0
	v_mov_b32_e32 v114, v0
	v_mov_b32_e32 v115, v0
	v_mov_b32_e32 v116, v0
	v_mov_b32_e32 v117, v0
	v_mov_b32_e32 v118, v0
	v_mov_b32_e32 v119, v0
	v_mov_b32_e32 v72, v0
	v_mov_b32_e32 v73, v0
	v_mov_b32_e32 v74, v0
	v_mov_b32_e32 v75, v0
	v_mov_b32_e32 v76, v0
	v_mov_b32_e32 v77, v0
	v_mov_b32_e32 v78, v0
	v_mov_b32_e32 v79, v0
	v_mov_b32_e32 v88, v0
	v_mov_b32_e32 v89, v0
	v_mov_b32_e32 v90, v0
	v_mov_b32_e32 v91, v0
	v_mov_b32_e32 v92, v0
	v_mov_b32_e32 v93, v0
	v_mov_b32_e32 v94, v0
	v_mov_b32_e32 v95, v0
	v_mov_b32_e32 v104, v0
	v_mov_b32_e32 v105, v0
	v_mov_b32_e32 v106, v0
	v_mov_b32_e32 v107, v0
	v_mov_b32_e32 v108, v0
	v_mov_b32_e32 v109, v0
	v_mov_b32_e32 v110, v0
	v_mov_b32_e32 v111, v0
	v_mov_b32_e32 v120, v0
	v_mov_b32_e32 v121, v0
	v_mov_b32_e32 v122, v0
	v_mov_b32_e32 v123, v0
	v_mov_b32_e32 v124, v0
	v_mov_b32_e32 v125, v0
	v_mov_b32_e32 v126, v0
	v_mov_b32_e32 v127, v0
	s_nop 0
	s_nop 0
	s_nop 0
	s_nop 0
	s_nop 0
	s_nop 0
	s_nop 0

.LBB0_796:
	s_add_i32 m0, s5, 0x18000
	v_lshl_add_u64 v[0:1], v[0:1], 0, s[2:3]
	s_and_b32 s41, s24, 3
	s_lshl_b32 s43, s23, 6
	s_lshl_b32 s23, s23, 13
	s_waitcnt vmcnt(2)
	s_barrier
	global_load_lds_dwordx4 v[0:1], off
	v_lshl_add_u64 v[0:1], v[2:3], 0, s[2:3]
	s_add_i32 m0, s5, 0x1a000
	s_add_i32 s44, s5, 0x8000
	s_add_i32 s45, s5, 0xa000
	global_load_lds_dwordx4 v[0:1], off
	v_lshl_add_u64 v[0:1], v[6:7], 0, s[2:3]
	s_mov_b32 m0, s44
	s_add_u32 s24, s6, 0x80080
	global_load_lds_dwordx4 v[0:1], off
	v_lshl_add_u64 v[0:1], v[4:5], 0, s[2:3]
	s_mov_b32 m0, s45
	s_addc_u32 s25, s7, 0
	global_load_lds_dwordx4 v[0:1], off
	s_add_i32 m0, s5, 0x1c000
	v_lshl_add_u64 v[0:1], s[24:25], 0, v[128:129]
	global_load_lds_dwordx4 v[0:1], off
	v_lshl_add_u64 v[0:1], s[24:25], 0, v[130:131]
	s_add_i32 m0, s5, 0x1e000
	v_bitop3_b32 v8, v144, s23, v145 bitop3:0xde
	global_load_lds_dwordx4 v[0:1], off
	s_waitcnt vmcnt(6)
	v_lshl_or_b32 v9, s41, 12, v143
	v_mov_b32_e32 v0, 0
	s_add_i32 s49, s30, s22
	s_add_i32 s51, s31, s22
	s_add_i32 s57, s34, s22
	s_add_i32 s59, s35, s22
	v_lshl_add_u64 v[138:139], v[134:135], 0, s[20:21]
	v_lshl_add_u64 v[140:141], v[136:137], 0, s[20:21]
	s_mov_b32 s46, -2
	s_mov_b64 s[20:21], 0x7680080
	v_add_u32_e32 v146, s30, v9
	v_add_u32_e32 v147, s31, v9
	v_add_u32_e32 v148, 0, v8
	s_add_i32 s47, s5, 0xc000
	s_add_i32 s48, s5, 0xe000
	s_add_i32 s50, s49, 0x2000
	s_add_i32 s56, s51, 0x2000
	v_add_u32_e32 v149, s34, v9
	v_add_u32_e32 v150, s35, v9
	s_add_i32 s58, s57, 0x2000
	s_add_i32 s84, s59, 0x2000
	v_mov_b32_e32 v1, v0
	v_mov_b32_e32 v2, v0
	v_mov_b32_e32 v3, v0
	v_mov_b32_e32 v4, v0
	v_mov_b32_e32 v5, v0
	v_mov_b32_e32 v6, v0
	v_mov_b32_e32 v7, v0
	v_mov_b32_e32 v16, v0
	v_mov_b32_e32 v17, v0
	v_mov_b32_e32 v18, v0
	v_mov_b32_e32 v19, v0
	v_mov_b32_e32 v20, v0
	v_mov_b32_e32 v21, v0
	v_mov_b32_e32 v22, v0
	v_mov_b32_e32 v23, v0
	v_mov_b32_e32 v32, v0
	v_mov_b32_e32 v33, v0
	v_mov_b32_e32 v34, v0
	v_mov_b32_e32 v35, v0
	v_mov_b32_e32 v36, v0
	v_mov_b32_e32 v37, v0
	v_mov_b32_e32 v38, v0
	v_mov_b32_e32 v39, v0
	v_mov_b32_e32 v48, v0
	v_mov_b32_e32 v49, v0
	v_mov_b32_e32 v50, v0
	v_mov_b32_e32 v51, v0
	v_mov_b32_e32 v52, v0
	v_mov_b32_e32 v53, v0
	v_mov_b32_e32 v54, v0
	v_mov_b32_e32 v55, v0
	v_mov_b32_e32 v8, v0
	v_mov_b32_e32 v9, v0
	v_mov_b32_e32 v10, v0
	v_mov_b32_e32 v11, v0
	v_mov_b32_e32 v12, v0
	v_mov_b32_e32 v13, v0
	v_mov_b32_e32 v14, v0
	v_mov_b32_e32 v15, v0
	v_mov_b32_e32 v24, v0
	v_mov_b32_e32 v25, v0
	v_mov_b32_e32 v26, v0
	v_mov_b32_e32 v27, v0
	v_mov_b32_e32 v28, v0
	v_mov_b32_e32 v29, v0
	v_mov_b32_e32 v30, v0
	v_mov_b32_e32 v31, v0
	v_mov_b32_e32 v40, v0
	v_mov_b32_e32 v41, v0
	v_mov_b32_e32 v42, v0
	v_mov_b32_e32 v43, v0
	v_mov_b32_e32 v44, v0
	v_mov_b32_e32 v45, v0
	v_mov_b32_e32 v46, v0
	v_mov_b32_e32 v47, v0
	v_mov_b32_e32 v56, v0
	v_mov_b32_e32 v57, v0
	v_mov_b32_e32 v58, v0
	v_mov_b32_e32 v59, v0
	v_mov_b32_e32 v60, v0
	v_mov_b32_e32 v61, v0
	v_mov_b32_e32 v62, v0
	v_mov_b32_e32 v63, v0
	v_mov_b32_e32 v64, v0
	v_mov_b32_e32 v65, v0
	v_mov_b32_e32 v66, v0
	v_mov_b32_e32 v67, v0
	v_mov_b32_e32 v68, v0
	v_mov_b32_e32 v69, v0
	v_mov_b32_e32 v70, v0
	v_mov_b32_e32 v71, v0
	v_mov_b32_e32 v80, v0
	v_mov_b32_e32 v81, v0
	v_mov_b32_e32 v82, v0
	v_mov_b32_e32 v83, v0
	v_mov_b32_e32 v84, v0
	v_mov_b32_e32 v85, v0
	v_mov_b32_e32 v86, v0
	v_mov_b32_e32 v87, v0
	v_mov_b32_e32 v96, v0
	v_mov_b32_e32 v97, v0
	v_mov_b32_e32 v98, v0
	v_mov_b32_e32 v99, v0
	v_mov_b32_e32 v100, v0
	v_mov_b32_e32 v101, v0
	v_mov_b32_e32 v102, v0
	v_mov_b32_e32 v103, v0
	v_mov_b32_e32 v112, v0
	v_mov_b32_e32 v113, v0
	v_mov_b32_e32 v114, v0
	v_mov_b32_e32 v115, v0
	v_mov_b32_e32 v116, v0
	v_mov_b32_e32 v117, v0
	v_mov_b32_e32 v118, v0
	v_mov_b32_e32 v119, v0
	v_mov_b32_e32 v72, v0
	v_mov_b32_e32 v73, v0
	v_mov_b32_e32 v74, v0
	v_mov_b32_e32 v75, v0
	v_mov_b32_e32 v76, v0
	v_mov_b32_e32 v77, v0
	v_mov_b32_e32 v78, v0
	v_mov_b32_e32 v79, v0
	v_mov_b32_e32 v88, v0
	v_mov_b32_e32 v89, v0
	v_mov_b32_e32 v90, v0
	v_mov_b32_e32 v91, v0
	v_mov_b32_e32 v92, v0
	v_mov_b32_e32 v93, v0
	v_mov_b32_e32 v94, v0
	v_mov_b32_e32 v95, v0
	v_mov_b32_e32 v104, v0
	v_mov_b32_e32 v105, v0
	v_mov_b32_e32 v106, v0
	v_mov_b32_e32 v107, v0
	v_mov_b32_e32 v108, v0
	v_mov_b32_e32 v109, v0
	v_mov_b32_e32 v110, v0
	v_mov_b32_e32 v111, v0
	v_mov_b32_e32 v120, v0
	v_mov_b32_e32 v121, v0
	v_mov_b32_e32 v122, v0
	v_mov_b32_e32 v123, v0
	v_mov_b32_e32 v124, v0
	v_mov_b32_e32 v125, v0
	v_mov_b32_e32 v126, v0
	v_mov_b32_e32 v127, v0
	s_barrier
	s_nop 0
	s_nop 0
	s_nop 0
	s_nop 0
	s_nop 0
	s_nop 0
	s_nop 0

.LBB0_1057:
	s_add_i32 s41, s41, 1
	s_cmp_lt_i32 s41, s9
	s_mov_b64 s[24:25], s[12:13]
	s_cselect_b64 s[12:13], -1, 0
	s_cmp_eq_u32 s41, s9
	s_mov_b64 s[26:27], s[16:17]
	s_mov_b32 s44, s8
	s_cselect_b64 s[16:17], -1, 0
	s_min_i32 s8, s41, s9
	s_mul_i32 s8, s8, s92
	s_add_i32 s8, s8, s96
	s_min_i32 s8, s8, 0x9f
	s_ashr_i32 s22, s8, 31
	s_lshr_b32 s22, s22, 29
	s_add_i32 s22, s8, s22
	s_ashr_i32 s23, s22, 3
	s_and_b32 s22, s22, -8
	s_and_b64 s[16:17], s[16:17], s[4:5]
	s_sub_i32 s8, s8, s22
	s_cmp_lt_i32 s8, 0
	s_cselect_b32 s22, 21, 20
	s_mul_i32 s8, s8, s22
	s_add_i32 s8, s8, s23
	s_mul_hi_i32 s22, s8, 0x2aaaaaab
	s_lshr_b32 s23, s22, 31
	s_ashr_i32 s22, s22, 1
	s_add_i32 s22, s22, s23
	s_mul_i32 s28, s22, 3
	s_sub_i32 s23, 40, s28
	s_min_u32 s29, s23, 3
	s_mul_i32 s22, s22, 12
	s_sub_i32 s46, s8, s22
	v_cvt_f32_ubyte0_e32 v1, s29
	v_cvt_f32_i32_e32 v0, s46
	v_rcp_iflag_f32_e32 v2, v1
	s_ashr_i32 s8, s46, 30
	s_or_b32 s8, s8, 1
	s_mov_b32 s45, s34
	v_mul_f32_e32 v2, v0, v2
	v_trunc_f32_e32 v2, v2
	v_fma_f32 v0, -v2, v1, v0
	v_cvt_i32_f32_e32 v2, v2
	v_cmp_ge_f32_e64 s[22:23], |v0|, v1
	s_and_b64 s[22:23], s[22:23], exec
	s_cselect_b32 s8, s8, 0
	v_readfirstlane_b32 s22, v2
	s_add_i32 s8, s22, s8
	s_mul_i32 s22, s8, s29
	s_sub_i32 s22, s46, s22
	s_sext_i32_i8 s22, s22
	s_add_i32 s34, s28, s22
	s_or_b64 s[22:23], s[12:13], s[16:17]
	s_lshl_b32 s12, s34, 8
	s_ashr_i32 s13, s12, 31
	s_lshl_b64 s[12:13], s[12:13], 11
	s_add_u32 s12, s6, s12
	s_addc_u32 s13, s7, s13
	s_and_b64 s[16:17], s[22:23], exec
	s_cselect_b32 s46, s13, s25
	s_cselect_b32 s47, s12, s24
	s_bfe_i64 s[16:17], s[8:9], 0x80000
	s_lshl_b64 s[16:17], s[16:17], 19
	s_add_u32 s16, s30, s16
	s_addc_u32 s17, s31, s17
	s_and_b64 s[28:29], s[22:23], exec
	s_cselect_b32 s48, s17, s27
	s_cselect_b32 s49, s16, s26
	s_add_u32 s24, s24, 0x40080
	s_addc_u32 s25, s25, 0
	s_add_u32 s50, s26, 0x100
	v_mov_b32_e32 v0, 0
	s_addc_u32 s51, s27, 0
	s_mov_b32 s56, -2
	v_mov_b32_e32 v1, v0
	v_mov_b32_e32 v2, v0
	v_mov_b32_e32 v3, v0
	v_mov_b32_e32 v4, v0
	v_mov_b32_e32 v5, v0
	v_mov_b32_e32 v6, v0
	v_mov_b32_e32 v7, v0
	v_mov_b32_e32 v16, v0
	v_mov_b32_e32 v17, v0
	v_mov_b32_e32 v18, v0
	v_mov_b32_e32 v19, v0
	v_mov_b32_e32 v20, v0
	v_mov_b32_e32 v21, v0
	v_mov_b32_e32 v22, v0
	v_mov_b32_e32 v23, v0
	v_mov_b32_e32 v32, v0
	v_mov_b32_e32 v33, v0
	v_mov_b32_e32 v34, v0
	v_mov_b32_e32 v35, v0
	v_mov_b32_e32 v36, v0
	v_mov_b32_e32 v37, v0
	v_mov_b32_e32 v38, v0
	v_mov_b32_e32 v39, v0
	v_mov_b32_e32 v48, v0
	v_mov_b32_e32 v49, v0
	v_mov_b32_e32 v50, v0
	v_mov_b32_e32 v51, v0
	v_mov_b32_e32 v52, v0
	v_mov_b32_e32 v53, v0
	v_mov_b32_e32 v54, v0
	v_mov_b32_e32 v55, v0
	v_mov_b32_e32 v8, v0
	v_mov_b32_e32 v9, v0
	v_mov_b32_e32 v10, v0
	v_mov_b32_e32 v11, v0
	v_mov_b32_e32 v12, v0
	v_mov_b32_e32 v13, v0
	v_mov_b32_e32 v14, v0
	v_mov_b32_e32 v15, v0
	v_mov_b32_e32 v24, v0
	v_mov_b32_e32 v25, v0
	v_mov_b32_e32 v26, v0
	v_mov_b32_e32 v27, v0
	v_mov_b32_e32 v28, v0
	v_mov_b32_e32 v29, v0
	v_mov_b32_e32 v30, v0
	v_mov_b32_e32 v31, v0
	v_mov_b32_e32 v40, v0
	v_mov_b32_e32 v41, v0
	v_mov_b32_e32 v42, v0
	v_mov_b32_e32 v43, v0
	v_mov_b32_e32 v44, v0
	v_mov_b32_e32 v45, v0
	v_mov_b32_e32 v46, v0
	v_mov_b32_e32 v47, v0
	v_mov_b32_e32 v56, v0
	v_mov_b32_e32 v57, v0
	v_mov_b32_e32 v58, v0
	v_mov_b32_e32 v59, v0
	v_mov_b32_e32 v60, v0
	v_mov_b32_e32 v61, v0
	v_mov_b32_e32 v62, v0
	v_mov_b32_e32 v63, v0
	v_mov_b32_e32 v64, v0
	v_mov_b32_e32 v65, v0
	v_mov_b32_e32 v66, v0
	v_mov_b32_e32 v67, v0
	v_mov_b32_e32 v68, v0
	v_mov_b32_e32 v69, v0
	v_mov_b32_e32 v70, v0
	v_mov_b32_e32 v71, v0
	v_mov_b32_e32 v80, v0
	v_mov_b32_e32 v81, v0
	v_mov_b32_e32 v82, v0
	v_mov_b32_e32 v83, v0
	v_mov_b32_e32 v84, v0
	v_mov_b32_e32 v85, v0
	v_mov_b32_e32 v86, v0
	v_mov_b32_e32 v87, v0
	v_mov_b32_e32 v96, v0
	s_waitcnt lgkmcnt(0)
	v_mov_b32_e32 v97, v0
	v_mov_b32_e32 v98, v0
	v_mov_b32_e32 v99, v0
	v_mov_b32_e32 v100, v0
	v_mov_b32_e32 v101, v0
	v_mov_b32_e32 v102, v0
	v_mov_b32_e32 v103, v0
	v_mov_b32_e32 v112, v0
	v_mov_b32_e32 v113, v0
	v_mov_b32_e32 v114, v0
	v_mov_b32_e32 v115, v0
	v_mov_b32_e32 v116, v0
	v_mov_b32_e32 v117, v0
	v_mov_b32_e32 v118, v0
	v_mov_b32_e32 v119, v0
	v_mov_b32_e32 v72, v0
	v_mov_b32_e32 v73, v0
	v_mov_b32_e32 v74, v0
	v_mov_b32_e32 v75, v0
	v_mov_b32_e32 v76, v0
	v_mov_b32_e32 v77, v0
	v_mov_b32_e32 v78, v0
	v_mov_b32_e32 v79, v0
	v_mov_b32_e32 v88, v0
	v_mov_b32_e32 v89, v0
	v_mov_b32_e32 v90, v0
	v_mov_b32_e32 v91, v0
	v_mov_b32_e32 v92, v0
	v_mov_b32_e32 v93, v0
	v_mov_b32_e32 v94, v0
	v_mov_b32_e32 v95, v0
	v_mov_b32_e32 v104, v0
	v_mov_b32_e32 v105, v0
	v_mov_b32_e32 v106, v0
	v_mov_b32_e32 v107, v0
	v_mov_b32_e32 v108, v0
	v_mov_b32_e32 v109, v0
	v_mov_b32_e32 v110, v0
	v_mov_b32_e32 v111, v0
	v_mov_b32_e32 v120, v0
	v_mov_b32_e32 v121, v0
	v_mov_b32_e32 v122, v0
	v_mov_b32_e32 v123, v0
	v_mov_b32_e32 v124, v0
	v_mov_b32_e32 v125, v0
	v_mov_b32_e32 v126, v0
	v_mov_b32_e32 v127, v0
	s_nop 0
	s_nop 0
	s_nop 0
	s_nop 0
	s_nop 0
	s_nop 0
	s_nop 0
	s_nop 0
	s_nop 0
	s_nop 0
	s_nop 0
	s_nop 0
	s_nop 0
	s_nop 0

.LBB0_1130:
	s_cmp_lt_i32 s76, 1
	s_cselect_b64 s[26:27], -1, 0
	s_add_u32 s34, s34, 0x80080
	s_addc_u32 s35, s35, 0
	v_mov_b32_e32 v2, v0
	v_mov_b32_e32 v3, v0
	s_add_u32 s18, s2, 0x100
	v_mov_b32_e32 v1, v0
	v_mov_b32_e32 v84, 0
	v_mov_b64_e32 v[6:7], v[2:3]
	v_mov_b64_e32 v[10:11], v[2:3]
	v_mov_b64_e32 v[22:23], v[2:3]
	v_mov_b64_e32 v[26:27], v[2:3]
	v_mov_b64_e32 v[38:39], v[2:3]
	v_mov_b64_e32 v[42:43], v[2:3]
	v_mov_b64_e32 v[54:55], v[2:3]
	v_mov_b64_e32 v[58:59], v[2:3]
	v_mov_b64_e32 v[14:15], v[2:3]
	v_mov_b64_e32 v[18:19], v[2:3]
	v_mov_b64_e32 v[30:31], v[2:3]
	v_mov_b64_e32 v[34:35], v[2:3]
	v_mov_b64_e32 v[46:47], v[2:3]
	v_mov_b64_e32 v[50:51], v[2:3]
	v_mov_b64_e32 v[62:63], v[2:3]
	v_mov_b64_e32 v[66:67], v[2:3]
	v_mov_b64_e32 v[70:71], v[2:3]
	v_mov_b64_e32 v[74:75], v[2:3]
	v_mov_b64_e32 v[78:79], v[2:3]
	v_mov_b64_e32 v[82:83], v[2:3]
	v_mov_b64_e32 v[94:95], v[2:3]
	v_mov_b64_e32 v[98:99], v[2:3]
	v_mov_b64_e32 v[110:111], v[2:3]
	v_mov_b64_e32 v[114:115], v[2:3]
	s_addc_u32 s41, s3, 0
	s_mov_b32 s77, -2
	v_cndmask_b32_e64 v217, 0, 1, s[26:27]
	v_mov_b64_e32 v[4:5], v[0:1]
	v_mov_b64_e32 v[8:9], v[0:1]
	v_mov_b64_e32 v[20:21], v[0:1]
	v_mov_b64_e32 v[24:25], v[0:1]
	v_mov_b64_e32 v[36:37], v[0:1]
	v_mov_b64_e32 v[40:41], v[0:1]
	v_mov_b64_e32 v[52:53], v[0:1]
	v_mov_b64_e32 v[56:57], v[0:1]
	v_mov_b64_e32 v[12:13], v[0:1]
	v_mov_b64_e32 v[16:17], v[0:1]
	v_mov_b64_e32 v[28:29], v[0:1]
	v_mov_b64_e32 v[32:33], v[0:1]
	v_mov_b64_e32 v[44:45], v[0:1]
	v_mov_b64_e32 v[48:49], v[0:1]
	v_mov_b64_e32 v[60:61], v[0:1]
	v_mov_b64_e32 v[64:65], v[0:1]
	v_mov_b64_e32 v[68:69], v[0:1]
	v_mov_b64_e32 v[72:73], v[0:1]
	v_mov_b64_e32 v[76:77], v[0:1]
	v_mov_b64_e32 v[80:81], v[0:1]
	v_mov_b64_e32 v[92:93], v[0:1]
	v_mov_b64_e32 v[96:97], v[0:1]
	v_mov_b64_e32 v[108:109], v[0:1]
	v_mov_b64_e32 v[112:113], v[0:1]
	v_mov_b32_e32 v85, v84
	v_mov_b32_e32 v86, v84
	v_mov_b32_e32 v87, v84
	v_mov_b32_e32 v88, v84
	v_mov_b32_e32 v89, v84
	v_mov_b32_e32 v90, v84
	v_mov_b32_e32 v91, v84
	v_mov_b32_e32 v100, v84
	v_mov_b32_e32 v101, v84
	v_mov_b32_e32 v102, v84
	v_mov_b32_e32 v103, v84
	v_mov_b32_e32 v104, v84
	v_mov_b32_e32 v105, v84
	v_mov_b32_e32 v106, v84
	v_mov_b32_e32 v107, v84
	v_mov_b32_e32 v116, v84
	v_mov_b32_e32 v117, v84
	v_mov_b32_e32 v118, v84
	v_mov_b32_e32 v119, v84
	v_mov_b32_e32 v120, v84
	v_mov_b32_e32 v121, v84
	v_mov_b32_e32 v122, v84
	v_mov_b32_e32 v123, v84
	v_mov_b32_e32 v124, v84
	v_mov_b32_e32 v125, v84
	v_mov_b32_e32 v126, v84
	v_mov_b32_e32 v127, v84
	v_mov_b32_e32 v128, v84
	v_mov_b32_e32 v129, v84
	v_mov_b32_e32 v130, v84
	v_mov_b32_e32 v131, v84
	s_branch .LBB0_1132
	s_nop 0
	s_nop 0
	s_nop 0
	s_nop 0
	s_nop 0
	s_nop 0
	s_nop 0
	s_nop 0
	s_nop 0
	s_nop 0
	s_nop 0
	s_nop 0

.Lq5_entry:
	v_mov_b32_e32 v4, 0
	v_mov_b32_e32 v5, 0
	v_mov_b32_e32 v6, 0
	v_mov_b32_e32 v7, 0
	v_mov_b32_e32 v8, 0
	v_mov_b32_e32 v9, 0
	v_mov_b32_e32 v10, 0
	v_mov_b32_e32 v11, 0
	v_mov_b32_e32 v12, 0
	v_mov_b32_e32 v13, 0
	v_mov_b32_e32 v14, 0
	v_mov_b32_e32 v15, 0
	v_mov_b32_e32 v16, 0
	v_mov_b32_e32 v17, 0
	v_mov_b32_e32 v18, 0
	v_mov_b32_e32 v19, 0
	v_mov_b32_e32 v20, 0
	v_mov_b32_e32 v21, 0
	v_mov_b32_e32 v22, 0
	v_mov_b32_e32 v23, 0
	v_mov_b32_e32 v24, 0
	v_mov_b32_e32 v25, 0
	v_mov_b32_e32 v26, 0
	v_mov_b32_e32 v27, 0
	v_mov_b32_e32 v28, 0
	v_mov_b32_e32 v29, 0
	v_mov_b32_e32 v30, 0
	v_mov_b32_e32 v31, 0
	v_mov_b32_e32 v32, 0
	v_mov_b32_e32 v33, 0
	v_mov_b32_e32 v34, 0
	v_mov_b32_e32 v35, 0
	v_mov_b32_e32 v36, 0
	v_mov_b32_e32 v37, 0
	v_mov_b32_e32 v38, 0
	v_mov_b32_e32 v39, 0
	v_mov_b32_e32 v40, 0
	v_mov_b32_e32 v41, 0
	v_mov_b32_e32 v42, 0
	v_mov_b32_e32 v43, 0
	v_mov_b32_e32 v44, 0
	v_mov_b32_e32 v45, 0
	v_mov_b32_e32 v46, 0
	v_mov_b32_e32 v47, 0
	v_mov_b32_e32 v48, 0
	v_mov_b32_e32 v49, 0
	v_mov_b32_e32 v50, 0
	v_mov_b32_e32 v51, 0
	s_branch .Lq5_top
	s_nop 0
	s_nop 0
	s_nop 0
	s_nop 0
	s_nop 0

.LBB0_1281:
	s_cmp_lt_i32 s79, 1
	s_cselect_b64 s[34:35], -1, 0
	s_add_u32 s38, s38, 0x80080
	s_addc_u32 s39, s39, 0
	v_mov_b32_e32 v2, v0
	v_mov_b32_e32 v3, v0
	s_add_u32 s16, s4, 0x100
	v_mov_b32_e32 v1, v0
	v_mov_b32_e32 v112, 0
	v_mov_b64_e32 v[6:7], v[2:3]
	v_mov_b64_e32 v[10:11], v[2:3]
	v_mov_b64_e32 v[22:23], v[2:3]
	v_mov_b64_e32 v[26:27], v[2:3]
	v_mov_b64_e32 v[38:39], v[2:3]
	v_mov_b64_e32 v[42:43], v[2:3]
	v_mov_b64_e32 v[54:55], v[2:3]
	v_mov_b64_e32 v[58:59], v[2:3]
	v_mov_b64_e32 v[14:15], v[2:3]
	v_mov_b64_e32 v[18:19], v[2:3]
	v_mov_b64_e32 v[30:31], v[2:3]
	v_mov_b64_e32 v[34:35], v[2:3]
	v_mov_b64_e32 v[46:47], v[2:3]
	v_mov_b64_e32 v[50:51], v[2:3]
	v_mov_b64_e32 v[62:63], v[2:3]
	v_mov_b64_e32 v[66:67], v[2:3]
	v_mov_b64_e32 v[90:91], v[2:3]
	v_mov_b64_e32 v[106:107], v[2:3]
	v_mov_b64_e32 v[110:111], v[2:3]
	v_mov_b64_e32 v[118:119], v[2:3]
	v_mov_b64_e32 v[126:127], v[2:3]
	v_mov_b64_e32 v[130:131], v[2:3]
	v_mov_b64_e32 v[142:143], v[2:3]
	v_mov_b64_e32 v[146:147], v[2:3]
	s_addc_u32 s27, s5, 0
	s_mov_b32 s84, -2
	v_cndmask_b32_e64 v251, 0, 1, s[34:35]
	v_mov_b64_e32 v[4:5], v[0:1]
	v_mov_b64_e32 v[8:9], v[0:1]
	v_mov_b64_e32 v[20:21], v[0:1]
	v_mov_b64_e32 v[24:25], v[0:1]
	v_mov_b64_e32 v[36:37], v[0:1]
	v_mov_b64_e32 v[40:41], v[0:1]
	v_mov_b64_e32 v[52:53], v[0:1]
	v_mov_b64_e32 v[56:57], v[0:1]
	v_mov_b64_e32 v[12:13], v[0:1]
	v_mov_b64_e32 v[16:17], v[0:1]
	v_mov_b64_e32 v[28:29], v[0:1]
	v_mov_b64_e32 v[32:33], v[0:1]
	v_mov_b64_e32 v[44:45], v[0:1]
	v_mov_b64_e32 v[48:49], v[0:1]
	v_mov_b64_e32 v[60:61], v[0:1]
	v_mov_b64_e32 v[64:65], v[0:1]
	v_mov_b64_e32 v[88:89], v[0:1]
	v_mov_b64_e32 v[104:105], v[0:1]
	v_mov_b64_e32 v[108:109], v[0:1]
	v_mov_b64_e32 v[116:117], v[0:1]
	v_mov_b64_e32 v[124:125], v[0:1]
	v_mov_b64_e32 v[128:129], v[0:1]
	v_mov_b64_e32 v[140:141], v[0:1]
	v_mov_b64_e32 v[144:145], v[0:1]
	v_mov_b32_e32 v113, v112
	v_mov_b32_e32 v114, v112
	v_mov_b32_e32 v115, v112
	v_mov_b32_e32 v120, v112
	v_mov_b32_e32 v121, v112
	v_mov_b32_e32 v122, v112
	v_mov_b32_e32 v123, v112
	v_mov_b32_e32 v132, v112
	v_mov_b32_e32 v133, v112
	v_mov_b32_e32 v134, v112
	v_mov_b32_e32 v135, v112
	v_mov_b32_e32 v136, v112
	v_mov_b32_e32 v137, v112
	v_mov_b32_e32 v138, v112
	v_mov_b32_e32 v139, v112
	v_mov_b32_e32 v148, v112
	v_mov_b32_e32 v149, v112
	v_mov_b32_e32 v150, v112
	v_mov_b32_e32 v151, v112
	v_mov_b32_e32 v152, v112
	v_mov_b32_e32 v153, v112
	v_mov_b32_e32 v154, v112
	v_mov_b32_e32 v155, v112
	v_mov_b32_e32 v156, v112
	v_mov_b32_e32 v157, v112
	v_mov_b32_e32 v158, v112
	v_mov_b32_e32 v159, v112
	v_mov_b32_e32 v160, v112
	v_mov_b32_e32 v161, v112
	v_mov_b32_e32 v162, v112
	v_mov_b32_e32 v163, v112
	s_branch .LBB0_1283
	s_nop 0
	s_nop 0
	s_nop 0
	s_nop 0
	s_nop 0
	s_nop 0
	s_nop 0
	s_nop 0
	s_nop 0

.Lq6_entry:
	v_mov_b32_e32 v4, 0
	v_mov_b32_e32 v5, 0
	v_mov_b32_e32 v6, 0
	v_mov_b32_e32 v7, 0
	v_mov_b32_e32 v8, 0
	v_mov_b32_e32 v9, 0
	v_mov_b32_e32 v10, 0
	v_mov_b32_e32 v11, 0
	v_mov_b32_e32 v12, 0
	v_mov_b32_e32 v13, 0
	v_mov_b32_e32 v14, 0
	v_mov_b32_e32 v15, 0
	v_mov_b32_e32 v16, 0
	v_mov_b32_e32 v17, 0
	v_mov_b32_e32 v18, 0
	v_mov_b32_e32 v19, 0
	v_mov_b32_e32 v20, 0
	v_mov_b32_e32 v21, 0
	v_mov_b32_e32 v22, 0
	v_mov_b32_e32 v23, 0
	v_mov_b32_e32 v24, 0
	v_mov_b32_e32 v25, 0
	v_mov_b32_e32 v26, 0
	v_mov_b32_e32 v27, 0
	v_mov_b32_e32 v28, 0
	v_mov_b32_e32 v29, 0
	v_mov_b32_e32 v30, 0
	v_mov_b32_e32 v31, 0
	v_mov_b32_e32 v32, 0
	v_mov_b32_e32 v33, 0
	v_mov_b32_e32 v34, 0
	v_mov_b32_e32 v35, 0
	v_mov_b32_e32 v36, 0
	v_mov_b32_e32 v37, 0
	v_mov_b32_e32 v38, 0
	v_mov_b32_e32 v39, 0
	v_mov_b32_e32 v40, 0
	v_mov_b32_e32 v41, 0
	v_mov_b32_e32 v42, 0
	v_mov_b32_e32 v43, 0
	v_mov_b32_e32 v44, 0
	v_mov_b32_e32 v45, 0
	v_mov_b32_e32 v46, 0
	v_mov_b32_e32 v47, 0
	v_mov_b32_e32 v48, 0
	v_mov_b32_e32 v49, 0
	v_mov_b32_e32 v50, 0
	v_mov_b32_e32 v51, 0
	s_branch .Lq6_top
	s_nop 0
	s_nop 0
	s_nop 0
	s_nop 0
	s_nop 0
	s_nop 0
	s_nop 0

.LBB0_1390:
	s_mul_i32 s9, s6, s9
	s_sub_i32 s9, s13, s9
	s_sext_i32_i16 s9, s9
	s_add_i32 s7, s7, s9
	s_lshl_b32 s20, s7, 8
	s_ashr_i32 s21, s20, 31
	s_lshl_b64 s[20:21], s[20:21], 12
	s_add_u32 s86, s80, s20
	v_readlane_b32 s9, v253, 50
	s_addc_u32 s87, s9, s21
	s_and_b64 s[18:19], s[18:19], exec
	s_cselect_b32 s9, s87, s15
	s_cselect_b32 s13, s86, s14
	s_add_u32 s14, s14, 0x80080
	s_addc_u32 s15, s15, 0
	s_add_u32 s20, s16, 0x100
	v_mov_b32_e32 v84, 0
	s_addc_u32 s21, s17, 0
	s_mov_b32 s22, -2
	v_mov_b32_e32 v85, v84
	v_mov_b32_e32 v86, v84
	v_mov_b32_e32 v87, v84
	v_mov_b32_e32 v56, v84
	v_mov_b32_e32 v57, v84
	v_mov_b32_e32 v58, v84
	v_mov_b32_e32 v59, v84
	v_mov_b32_e32 v128, v84
	v_mov_b32_e32 v129, v84
	v_mov_b32_e32 v130, v84
	v_mov_b32_e32 v131, v84
	v_mov_b32_e32 v80, v84
	v_mov_b32_e32 v81, v84
	v_mov_b32_e32 v82, v84
	v_mov_b32_e32 v83, v84
	v_mov_b32_e32 v132, v84
	v_mov_b32_e32 v133, v84
	v_mov_b32_e32 v134, v84
	v_mov_b32_e32 v135, v84
	v_mov_b32_e32 v60, v84
	v_mov_b32_e32 v61, v84
	v_mov_b32_e32 v62, v84
	v_mov_b32_e32 v63, v84
	v_mov_b32_e32 v124, v84
	v_mov_b32_e32 v125, v84
	v_mov_b32_e32 v126, v84
	v_mov_b32_e32 v127, v84
	v_mov_b32_e32 v52, v84
	v_mov_b32_e32 v53, v84
	v_mov_b32_e32 v54, v84
	v_mov_b32_e32 v55, v84
	v_mov_b32_e32 v88, v84
	v_mov_b32_e32 v89, v84
	v_mov_b32_e32 v90, v84
	v_mov_b32_e32 v91, v84
	v_mov_b32_e32 v16, v84
	v_mov_b32_e32 v17, v84
	v_mov_b32_e32 v18, v84
	v_mov_b32_e32 v19, v84
	v_mov_b32_e32 v120, v84
	v_mov_b32_e32 v121, v84
	v_mov_b32_e32 v122, v84
	v_mov_b32_e32 v123, v84
	v_mov_b32_e32 v48, v84
	v_mov_b32_e32 v49, v84
	v_mov_b32_e32 v50, v84
	v_mov_b32_e32 v51, v84
	v_mov_b32_e32 v92, v84
	v_mov_b32_e32 v93, v84
	v_mov_b32_e32 v94, v84
	v_mov_b32_e32 v95, v84
	v_mov_b32_e32 v20, v84
	v_mov_b32_e32 v21, v84
	v_mov_b32_e32 v22, v84
	v_mov_b32_e32 v23, v84
	v_mov_b32_e32 v0, v84
	v_mov_b32_e32 v1, v84
	v_mov_b32_e32 v2, v84
	v_mov_b32_e32 v3, v84
	v_mov_b32_e32 v64, v84
	v_mov_b32_e32 v65, v84
	v_mov_b32_e32 v66, v84
	v_mov_b32_e32 v67, v84
	v_mov_b32_e32 v8, v84
	v_mov_b32_e32 v9, v84
	v_mov_b32_e32 v10, v84
	v_mov_b32_e32 v11, v84
	v_mov_b32_e32 v72, v84
	v_mov_b32_e32 v73, v84
	v_mov_b32_e32 v74, v84
	v_mov_b32_e32 v75, v84
	v_mov_b32_e32 v4, v84
	v_mov_b32_e32 v5, v84
	v_mov_b32_e32 v6, v84
	v_mov_b32_e32 v7, v84
	v_mov_b32_e32 v68, v84
	v_mov_b32_e32 v69, v84
	v_mov_b32_e32 v70, v84
	v_mov_b32_e32 v71, v84
	v_mov_b32_e32 v12, v84
	v_mov_b32_e32 v13, v84
	v_mov_b32_e32 v14, v84
	v_mov_b32_e32 v15, v84
	v_mov_b32_e32 v76, v84
	v_mov_b32_e32 v77, v84
	v_mov_b32_e32 v78, v84
	v_mov_b32_e32 v79, v84
	v_mov_b32_e32 v32, v84
	v_mov_b32_e32 v33, v84
	v_mov_b32_e32 v34, v84
	v_mov_b32_e32 v35, v84
	v_mov_b32_e32 v104, v84
	v_mov_b32_e32 v105, v84
	v_mov_b32_e32 v106, v84
	v_mov_b32_e32 v107, v84
	v_mov_b32_e32 v40, v84
	v_mov_b32_e32 v41, v84
	v_mov_b32_e32 v42, v84
	v_mov_b32_e32 v43, v84
	v_mov_b32_e32 v112, v84
	v_mov_b32_e32 v113, v84
	v_mov_b32_e32 v114, v84
	v_mov_b32_e32 v115, v84
	v_mov_b32_e32 v136, v84
	v_mov_b32_e32 v137, v84
	v_mov_b32_e32 v138, v84
	v_mov_b32_e32 v139, v84
	v_mov_b32_e32 v36, v84
	v_mov_b32_e32 v37, v84
	v_mov_b32_e32 v38, v84
	v_mov_b32_e32 v39, v84
	v_mov_b32_e32 v108, v84
	v_mov_b32_e32 v109, v84
	v_mov_b32_e32 v110, v84
	v_mov_b32_e32 v111, v84
	v_mov_b32_e32 v44, v84
	v_mov_b32_e32 v45, v84
	v_mov_b32_e32 v46, v84
	v_mov_b32_e32 v47, v84
	v_mov_b32_e32 v116, v84
	v_mov_b32_e32 v117, v84
	v_mov_b32_e32 v118, v84
	v_mov_b32_e32 v119, v84
	v_mov_b32_e32 v140, v84
	v_mov_b32_e32 v141, v84
	v_mov_b32_e32 v142, v84
	v_mov_b32_e32 v143, v84
	s_nop 0
	s_nop 0
	s_nop 0
	s_nop 0
	s_nop 0
	s_nop 0
	s_nop 0
	s_nop 0
	s_nop 0
